# static s_setprio 1 kept on waves 0-3 (the faster of the two halves when built both ways) for scan+attention phases; NAT local-tile loop exponent as one fma per element
# baseline (speedup 1.0000x reference)
; DI int tid_opaque() { int t = threadIdx.x; asm volatile("" : "+v"(t)); return t; }
; template <bool SWA>
; DI void attn_phase(const Ctx& a, LAS unsigned char* lds) {
;     ...
;     const int tid = tid_opaque(); const int lane = tid & 63, fr = lane & 15, fq = lane >> 4, w = tid >> 6;
;     constexpr int LDQ = SWA ? 1280 : 2048, HD = SWA ? 256 : 1024, NLAT = 2048, NCTX = 128;
;     const int G_ = gridDim.x, vb_ = (G_ % 8 == 0) ? (int)(blockIdx.x % 8) * (G_ / 8) + (int)(blockIdx.x / 8) : (int)blockIdx.x;
;     for (int item = vb_; item < NLAT + NCTX; item += G_) {
;         int b, kvh, hq, qbase, nloc, loc0 = 0;
;         int r = 0, cbk = 0, r0 = 0, cs = 0, rlo = 0, tq0 = 0;
;         const bool lat = item < NLAT;
;         if (lat) {
;             if (!SWA) { const int rp = item & 31; hq = (item >> 5) & 15; b = item >> 9; kvh = hq; r = 2 * rp + (w >> 2); cbk = w & 3; qbase = b * 4096 + r * 64 + 16 * cbk;
;                 r0 = r - 4 < 0 ? 0 : (r - 4 > 56 ? 56 : r - 4); cs = 16 * cbk - 8 < 0 ? 0 : (16 * cbk - 8 > 32 ? 32 : 16 * cbk - 8);
;                 rlo = 2 * rp - 4 < 0 ? 0 : (2 * rp - 4 > 56 ? 56 : 2 * rp - 4); const int rh = 2 * rp - 3 < 0 ? 0 : (2 * rp - 3 > 56 ? 56 : 2 * rp - 3);
;                 nloc = rh + 8 - rlo; loc0 = b * 4096 + rlo * 64; }
;             else { const int tb = item & 127; kvh = (item >> 7) & 3; b = item >> 9; hq = kvh * 4 + (w >> 1); tq0 = 32 * tb + 16 * (w & 1); qbase = b * 4096 + tq0;
;                 int ts = (32 * tb - 128) & ~63; if (ts < 0) ts = 0;
;                 int te = (32 * tb + 159) >> 6; if (te > 63) te = 63;
;                 nloc = te - (ts >> 6) + 1; loc0 = b * 4096 + ts; rlo = ts; }
;         } else {
;             const int i2 = item - NLAT;
;             if (!SWA) { const int hf = i2 & 1; hq = (i2 >> 1) & 15; b = i2 >> 5; kvh = hq; qbase = ML + b * 256 + 128 * hf + 16 * w; }
;             else { const int q8 = i2 & 7; kvh = (i2 >> 3) & 3; b = i2 >> 5; hq = kvh * 4 + (w >> 1); qbase = ML + b * 256 + 32 * q8 + 16 * (w & 1); }
;             nloc = 0;
;         }
;         const int koff = 1024 + kvh * 64, ntile = nloc + 4;
;         int nb_off[8]; float nb_mask[8];
;         if (!SWA) {
; #pragma unroll
;             for (int e = 0; e < 8; ++e) { const int col = cs + 16 * (e >> 2) + 4 * fq + (e & 3), ci = 16 * cbk + fr; const int c0 = ci - 8 < 0 ? 0 : (ci - 8 > 48 ? 48 : ci - 8);
.LBB0_61:
	v_readlane_b32 s0, v254, 57
	v_readlane_b32 s1, v254, 58
	s_mov_b64 s[30:31], -1
	s_and_b64 vcc, exec, s[0:1]
	s_cbranch_vccz .LBB0_192
	v_readlane_b32 s0, v254, 63
	v_readlane_b32 s1, v255, 0
	v_writelane_b32 v255, s16, 32
	s_and_b64 vcc, exec, s[0:1]
	s_nop 0
	v_writelane_b32 v255, s17, 33
	v_writelane_b32 v255, s10, 34
	s_nop 1
	v_writelane_b32 v255, s11, 35
	s_cbranch_vccz .LBB0_123
	v_readlane_b32 s0, v254, 49
	v_readlane_b32 s1, v254, 50
	s_andn2_b64 vcc, exec, s[0:1]
	s_cbranch_vccnz .LBB0_122
	v_readlane_b32 s0, v255, 1
	v_readlane_b32 s1, v255, 2
	s_and_b64 s[2:3], s[0:1], exec
	v_readlane_b32 s0, v255, 3
	s_cselect_b32 s2, s0, s82
	s_waitcnt vmcnt(1)
	v_mov_b32_e32 v0, v200
	s_cmpk_gt_i32 s2, 0x87f
	s_cbranch_scc1 .LBB0_122
	v_ashrrev_i32_e32 v1, 6, v0
	s_waitcnt vmcnt(0)
	v_lshrrev_b32_e32 v4, 4, v0
	v_and_b32_e32 v47, 15, v0
	v_and_b32_e32 v3, 63, v0
	v_bfe_u32 v5, v0, 4, 2
	v_ashrrev_i32_e32 v61, 7, v0
	v_lshlrev_b32_e32 v2, 4, v1
	v_ashrrev_i32_e32 v40, 3, v0
	v_xor_b32_e32 v4, v4, v0
	v_lshl_add_u32 v64, v1, 10, 0
	v_lshrrev_b32_e32 v1, 1, v0
	v_bfe_u32 v6, v0, 1, 3
	v_bfe_u32 v0, v0, 5, 1
	v_lshlrev_b32_e32 v4, 3, v4
	v_bitop3_b32 v7, v5, v1, 7 bitop3:0x78
	v_bitop3_b32 v1, v0, v1, 7 bitop3:0x78
	v_and_b32_e32 v62, 16, v2
	v_lshlrev_b32_e32 v2, 3, v5
	v_cmp_gt_u32_e32 vcc, 16, v3
	v_and_b32_e32 v4, 56, v4
	v_lshlrev_b32_e32 v3, 2, v3
	v_lshlrev_b32_e32 v70, 4, v1
	v_bitop3_b32 v1, v0, v6, 2 bitop3:0x36
	v_lshlrev_b32_e32 v146, 1, v4
	v_lshl_add_u32 v65, v47, 7, 0
	v_lshlrev_b32_e32 v66, 4, v7
	v_bitop3_b32 v7, v5, v6, 4 bitop3:0x36
	v_lshlrev_b32_e32 v46, 2, v5
	v_xor_b32_e32 v68, 64, v3
	v_xor_b32_e32 v69, 0x80, v3
	v_and_b32_e32 v3, 8, v2
	v_lshlrev_b32_e32 v71, 4, v1
	v_bitop3_b32 v1, v0, v6, 4 bitop3:0x36
	v_bitop3_b32 v0, v0, v6, 6 bitop3:0x36
	v_cndmask_b32_e64 v63, 0, 1.0, vcc
	v_ashrrev_i32_e32 v41, 31, v40
	v_lshl_add_u64 v[42:43], s[76:77], 0, v[146:147]
	v_lshl_add_u64 v[44:45], s[50:51], 0, v[146:147]
	v_lshlrev_b32_e32 v67, 4, v7
	v_lshlrev_b32_e32 v72, 4, v1
	v_lshlrev_b32_e32 v73, 4, v0
	v_add_u32_e32 v74, v65, v3
	v_add_u32_e32 v75, 0x100, v40
	v_lshlrev_b32_e32 v146, 1, v2
	v_lshlrev_b32_e32 v48, 1, v4
	v_lshlrev_b32_e32 v50, 1, v46
	v_readfirstlane_b32 s98, v200
	s_nop 3
	s_cmp_lt_u32 s98, 0x100
	s_cbranch_scc0 .Lprio_skip0
	s_setprio 1

; DI int tid_opaque() { int t = threadIdx.x; asm volatile("" : "+v"(t)); return t; }
; template <bool SWA>
; DI void attn_phase(const Ctx& a, LAS unsigned char* lds) {
;     ...
;     const int tid = tid_opaque(); const int lane = tid & 63, fr = lane & 15, fq = lane >> 4, w = tid >> 6;
;     constexpr int LDQ = SWA ? 1280 : 2048, HD = SWA ? 256 : 1024, NLAT = 2048, NCTX = 128;
;     const int G_ = gridDim.x, vb_ = (G_ % 8 == 0) ? (int)(blockIdx.x % 8) * (G_ / 8) + (int)(blockIdx.x / 8) : (int)blockIdx.x;
;     for (int item = vb_; item < NLAT + NCTX; item += G_) {
;         int b, kvh, hq, qbase, nloc, loc0 = 0;
;         int r = 0, cbk = 0, r0 = 0, cs = 0, rlo = 0, tq0 = 0;
;         const bool lat = item < NLAT;
;         if (lat) {
;             if (!SWA) { const int rp = item & 31; hq = (item >> 5) & 15; b = item >> 9; kvh = hq; r = 2 * rp + (w >> 2); cbk = w & 3; qbase = b * 4096 + r * 64 + 16 * cbk;
;                 r0 = r - 4 < 0 ? 0 : (r - 4 > 56 ? 56 : r - 4); cs = 16 * cbk - 8 < 0 ? 0 : (16 * cbk - 8 > 32 ? 32 : 16 * cbk - 8);
;                 rlo = 2 * rp - 4 < 0 ? 0 : (2 * rp - 4 > 56 ? 56 : 2 * rp - 4); const int rh = 2 * rp - 3 < 0 ? 0 : (2 * rp - 3 > 56 ? 56 : 2 * rp - 3);
;                 nloc = rh + 8 - rlo; loc0 = b * 4096 + rlo * 64; }
;             else { const int tb = item & 127; kvh = (item >> 7) & 3; b = item >> 9; hq = kvh * 4 + (w >> 1); tq0 = 32 * tb + 16 * (w & 1); qbase = b * 4096 + tq0;
;                 int ts = (32 * tb - 128) & ~63; if (ts < 0) ts = 0;
;                 int te = (32 * tb + 159) >> 6; if (te > 63) te = 63;
;                 nloc = te - (ts >> 6) + 1; loc0 = b * 4096 + ts; rlo = ts; }
;         } else {
;             const int i2 = item - NLAT;
;             if (!SWA) { const int hf = i2 & 1; hq = (i2 >> 1) & 15; b = i2 >> 5; kvh = hq; qbase = ML + b * 256 + 128 * hf + 16 * w; }
;             else { const int q8 = i2 & 7; kvh = (i2 >> 3) & 3; b = i2 >> 5; hq = kvh * 4 + (w >> 1); qbase = ML + b * 256 + 32 * q8 + 16 * (w & 1); }
;             nloc = 0;
;         }
;         const int koff = 1024 + kvh * 64, ntile = nloc + 4;
;         int nb_off[8]; float nb_mask[8];
;         if (!SWA) {
; #pragma unroll
;             for (int e = 0; e < 8; ++e) { const int col = cs + 16 * (e >> 2) + 4 * fq + (e & 3), ci = 16 * cbk + fr; const int c0 = ci - 8 < 0 ? 0 : (ci - 8 > 48 ? 48 : ci - 8);
.LBB0_123:
	s_andn2_b64 vcc, exec, s[30:31]
	s_cbranch_vccnz .LBB0_191
	v_readlane_b32 s0, v255, 1
	v_readlane_b32 s1, v255, 2
	s_and_b64 s[2:3], s[0:1], exec
	v_readlane_b32 s0, v255, 3
	s_cselect_b32 s17, s0, s82
	s_waitcnt vmcnt(0)
	v_mov_b32_e32 v41, v200
	s_cmpk_gt_i32 s17, 0x87f
	s_cbranch_scc1 .LBB0_191
	v_and_b32_e32 v1, 63, v41
	v_lshrrev_b32_e32 v2, 4, v41
	v_bfe_u32 v60, v41, 4, 2
	v_ashrrev_i32_e32 v3, 6, v41
	v_mov_b32_e32 v0, 0x4000
	v_xor_b32_e32 v2, v2, v41
	v_lshlrev_b32_e32 v1, 2, v1
	v_and_b32_e32 v59, 15, v41
	v_lshl_add_u32 v61, v3, 4, v0
	v_lshlrev_b32_e32 v0, 3, v60
	v_lshlrev_b32_e32 v2, 3, v2
	v_xor_b32_e32 v69, 64, v1
	v_xor_b32_e32 v70, 0x80, v1
	v_bfe_u32 v71, v41, 5, 1
	v_lshrrev_b32_e32 v1, 1, v41
	v_bfe_u32 v73, v41, 1, 3
	v_and_b32_e32 v63, 3, v3
	v_and_b32_e32 v2, 56, v2
	v_lshl_add_u32 v66, v3, 10, 0
	v_and_b32_e32 v72, 8, v0
	v_lshl_add_u32 v74, v59, 7, 0
	v_bitop3_b32 v3, v60, v1, 7 bitop3:0x78
	v_bitop3_b32 v4, v60, v73, 4 bitop3:0x36
	v_bitop3_b32 v1, v71, v1, 7 bitop3:0x78
	v_bitop3_b32 v5, v71, v73, 2 bitop3:0x36
	v_bitop3_b32 v6, v71, v73, 4 bitop3:0x36
	v_bitop3_b32 v7, v71, v73, 6 bitop3:0x36
	v_lshlrev_b32_e32 v64, 4, v63
	v_lshlrev_b32_e32 v40, 2, v60
	v_ashrrev_i32_e32 v42, 3, v41
	s_movk_i32 s3, 0x1d1
	v_lshlrev_b32_e32 v146, 1, v2
	v_lshlrev_b32_e32 v3, 4, v3
	v_lshlrev_b32_e32 v4, 4, v4
	v_lshlrev_b32_e32 v1, 4, v1
	v_lshlrev_b32_e32 v5, 4, v5
	v_lshlrev_b32_e32 v6, 4, v6
	v_lshlrev_b32_e32 v7, 4, v7
	v_add_u32_e32 v8, v74, v72
	v_ashrrev_i32_e32 v62, 8, v41
	v_add_u32_e32 v65, -8, v64
	v_cmp_gt_i32_e64 s[40:41], s3, v41
	v_ashrrev_i32_e32 v43, 31, v42
	v_lshl_add_u64 v[44:45], s[76:77], 0, v[146:147]
	v_lshl_add_u32 v67, v41, 2, 0
	v_lshl_add_u64 v[46:47], s[50:51], 0, v[146:147]
	v_or_b32_e32 v68, 4, v60
	v_lshlrev_b32_e32 v48, 1, v0
	v_lshlrev_b32_e32 v146, 1, v2
	v_lshlrev_b32_e32 v50, 1, v40
	v_add_u32_e32 v75, v74, v3
	v_add_u32_e32 v76, v74, v4
	v_add_u32_e32 v77, v8, v1
	v_add_u32_e32 v78, v8, v5
	v_add_u32_e32 v79, v8, v6
	v_add_u32_e32 v80, v8, v7
	v_readfirstlane_b32 s98, v200
	s_nop 3
	s_cmp_lt_u32 s98, 0x100
	s_cbranch_scc0 .Lprio_skip1
	s_setprio 1

; #define LAS __attribute__((address_space(3)))
; DI unsigned pk2(float lo, float hi) { const f32x2 v = {lo, hi}; const hbf16x2 b = __builtin_convertvector(v, hbf16x2); return __builtin_bit_cast(unsigned, b); }
; #define MFMA16(a, b, c) __builtin_amdgcn_mfma_f32_16x16x32_bf16((a), (b), (c), 0, 0, 0)
; template <bool SWA>
; DI void attn_phase(const Ctx& a, LAS unsigned char* lds) {
;     ...
;                 const float m_new = fmaxf(m_run, cmax);
;                 const float alpha = __builtin_amdgcn_exp2f((m_run - m_new) * LOG2E);
;                 float p[8], psum = 0.f;
; #pragma unroll
;                 for (int e = 0; e < 8; ++e) { p[e] = ok[e] ? __builtin_amdgcn_exp2f((sv[e] - m_new) * LOG2E) : 0.f; psum += p[e]; }
;                 l_run = l_run * alpha + psum; m_run = m_new;
;                 u32x4 pw; pw.x = pk2(p[0], p[1]); pw.y = pk2(p[2], p[3]); pw.z = pk2(p[4], p[5]); pw.w = pk2(p[6], p[7]);
;                 const bf16x8 pf = __builtin_bit_cast(bf16x8, pw);
;                 if (__builtin_amdgcn_ballot_w64(alpha != 1.f) != 0ull) {
; #pragma unroll
;                     for (int dt = 0; dt < 4; ++dt) o[dt] = o[dt] * alpha;
;                 }
;                 const int kc = (ko >> 3) + (fq >> 1), kb8 = (fq & 1) * 8;
; #pragma unroll
;                 for (int dt = 0; dt < 4; ++dt) {
;                     const int d = 16 * dt + fr, sw = (d >> 1) & 7;
;                     const s16x4 v0 = *(const LAS s16x4*)(lds + AT_V + buf * 8192 + d * 128 + ((kc ^ sw) << 4) + kb8);
;                     const s16x4 v1 = *(const LAS s16x4*)(lds + AT_V + buf * 8192 + d * 128 + (((kc + 2) ^ sw) << 4) + kb8);
;                     const bf16x8 vfr = __builtin_shufflevector(v0, v1, 0, 1, 2, 3, 4, 5, 6, 7);
;                     o[dt] = MFMA16(vfr, pf, o[dt]);
.LBB0_183:
	s_mov_b32 s98, 0x3fb8aa3b
	v_mul_f32_e32 v190, 0xbfb8aa3b, v89
	v_fma_f32 v97, v97, s98, v190
	v_fma_f32 v96, v96, s98, v190
	v_fma_f32 v95, v95, s98, v190
	v_fma_f32 v94, v94, s98, v190
	v_fma_f32 v93, v93, s98, v190
	v_fma_f32 v92, v92, s98, v190
	v_fma_f32 v91, v91, s98, v190
	v_fma_f32 v90, v90, s98, v190
	v_exp_f32_e32 v97, v97
	v_exp_f32_e32 v96, v96
	v_exp_f32_e32 v95, v95
	v_exp_f32_e32 v94, v94
	v_exp_f32_e32 v93, v93
	v_exp_f32_e32 v92, v92
	v_exp_f32_e32 v99, v91
	v_add_f32_e32 v98, 0, v97
	v_add_f32_e32 v98, v96, v98
	v_add_f32_e32 v98, v95, v98
	v_add_f32_e32 v98, v94, v98
	v_add_f32_e32 v98, v93, v98
	v_add_f32_e32 v98, v92, v98
	v_add_f32_e32 v91, v99, v98
	v_exp_f32_e32 v98, v90
	v_cvt_pk_bf16_f32 v90, v97, v96
	v_cvt_pk_bf16_f32 v92, v93, v92
	v_add_f32_e32 v106, v98, v91
	v_fmac_f32_e32 v106, v88, v24
	v_cvt_pk_bf16_f32 v91, v95, v94
	v_cvt_pk_bf16_f32 v93, v99, v98
	v_mov_b32_e32 v88, v106
	v_readlane_b32 s49, v255, 19
	v_mov_b32_e32 v49, v89
	s_waitcnt lgkmcnt(0)
	v_mfma_f32_16x16x32_bf16 v[20:23], v[140:143], v[90:93], v[20:23]
	v_mfma_f32_16x16x32_bf16 v[8:11], v[136:139], v[90:93], v[8:11]
	v_mfma_f32_16x16x32_bf16 v[16:19], v[160:163], v[90:93], v[16:19]
	v_mfma_f32_16x16x32_bf16 v[12:15], v[164:167], v[90:93], v[12:15]
	s_or_b64 exec, exec, s[42:43]
	s_mov_b64 s[42:43], -1
	s_and_b64 vcc, exec, s[30:31]
	s_cbranch_vccnz .LBB0_186

; #define LAS __attribute__((address_space(3)))
; DI int tid_opaque() { int t = threadIdx.x; asm volatile("" : "+v"(t)); return t; }
; DI void ret_chain_phase(const Ctx& a, LAS unsigned char* lds) {
;     ...
;     const int tid = tid_opaque(), wid = tid >> 6, lane = tid & 63, fr = lane & 15, fq = lane >> 4;
;     for (int cid = blockIdx.x; cid < 256; cid += gridDim.x) {
;         const int xq = cid & 7, yq = cid >> 3, grp = xq * 4 + (yq >> 3), vs = yq & 7;
;         const int dir = grp & 1, h = (grp >> 1) & 3, b = grp >> 3;
;         const float lg2 = dec[dir * 4 + h];
;         const bf16_t* KT = (const bf16_t*)(a.ws + (dir ? OFF_RKTB : OFF_RKTF));
;         bf16_t* O = (bf16_t*)(a.ws + OFF_ACT) + (dir ? (size_t)MT * 2048 : 0);
;         f32x4 accS[2][4];
; #pragma unroll
;         for (int i = 0; i < 2; ++i)
; #pragma unroll
;             for (int j = 0; j < 4; ++j) accS[i][j] = (f32x4){0.f, 0.f, 0.f, 0.f};
;         for (int i = tid; i < 32768 / 16; i += NTHREADS) *(LAS u32x4*)(lds + RC_SS + i * 16) = (u32x4){0u, 0u, 0u, 0u};
;         const int it = wid & 3, half = wid >> 2;
;         const int icol = 16 * it + fr;
;         const float qdec = __builtin_amdgcn_exp2f(lg2 * (float)(dir ? 64 - icol : icol + 1));
;         const float cdec = __builtin_amdgcn_exp2f(lg2 * 64.f);
;         float wdec[2][4];
; #pragma unroll
;         for (int j2 = 0; j2 < 2; ++j2)
; #pragma unroll
;             for (int r = 0; r < 4; ++r) { const int j = 16 * (2 * half + j2) + 4 * fq + r; const int dd = dir ? (j - icol) : (icol - j); const bool keep = dir ? (dd > 0) : (dd >= 0);
;                 wdec[j2][r] = keep ? __builtin_amdgcn_exp2f(lg2 * (float)dd) : 0.f; }
;         __syncthreads();
;         u32x4 pkt[4], pvt;
;     ...
;         const int qk_src = ((tid >> 5) * 1024 + h * 256 + (((tid & 31) ^ ((tid >> 5) & 15)) * 8)) * 2;
.LBB0_192:
	s_andn2_b64 vcc, exec, s[30:31]
	s_cbranch_vccnz .LBB0_213
	v_readlane_b32 s2, v252, 6
	v_readlane_b32 s3, v252, 7
	s_waitcnt vmcnt(0)
	v_mov_b32_e32 v0, v200
	s_andn2_b64 vcc, exec, s[2:3]
	s_cbranch_vccnz .LBB0_213
	v_readfirstlane_b32 s98, v200
	s_nop 3
	s_cmp_lt_u32 s98, 0x100
	s_cbranch_scc0 .Lprio_skip2
	s_setprio 1
